# v18 + phase E (GLU GEMM, hipcc-unrolled) ported to the LDS-DMA loop with per-MFMA-gap DMA/ds_read interleave
# speedup vs baseline: 1.0132x; 1.0028x over previous
.LBB0_864:
	s_and_b32 s6, s2, 0x1f80
	s_ashr_i32 s0, s45, 6
	s_lshl_b32 s40, s6, 11
	s_add_u32 s56, s88, s40
	s_addc_u32 s57, s89, 0
	s_ashr_i32 s1, s0, 31
	s_lshl_b64 s[0:1], s[0:1], 18
	s_add_u32 s58, s88, s0
	s_addc_u32 s59, s89, s1
	s_add_u32 s58, s58, 0x2280000
	s_addc_u32 s59, s59, 0
	s_mov_b64 s[0:1], vcc
	s_mov_b64 s[4:5], vcc
	s_mov_b64 s[0:1], vcc
	s_mov_b64 s[4:5], vcc
	s_mov_b64 s[0:1], vcc
	s_and_b32 s0, s45, 0xffffffc0
	s_ashr_i32 s1, s0, 31
	s_or_b32 s4, s6, 32
	s_add_i32 s45, s45, s92
	s_add_i32 s2, s2, s33
	s_cmpk_lt_i32 s45, 0x400
	v_readfirstlane_b32 s61, v168
	v_lshrrev_b32_e32 v64, 3, v168
	v_bfe_u32 v65, v168, 4, 3
	v_and_b32_e32 v66, 7, v168
	v_xor_b32_e32 v65, v65, v66
	v_lshlrev_b32_e32 v65, 4, v65
	s_lshr_b32 s61, s61, 6
	s_lshl_b32 s61, s61, 10
	s_movk_i32 s60, 0x800
	v_mul_lo_u32 v64, v64, s60
	v_add_u32_e32 v64, v64, v65
	v_add_u32_e32 v65, 0x10000, v64
	v_add_u32_e32 v66, 0x20000, v64
	v_add_u32_e32 v67, 0x30000, v64
	v_mov_b32_e32 v0, 0
	v_mov_b32_e32 v1, v0
	v_mov_b32_e32 v2, v0
	v_mov_b32_e32 v3, v0
	v_mov_b32_e32 v4, v0
	v_mov_b32_e32 v5, v0
	v_mov_b32_e32 v6, v0
	v_mov_b32_e32 v7, v0
	v_mov_b32_e32 v8, v0
	v_mov_b32_e32 v9, v0
	v_mov_b32_e32 v10, v0
	v_mov_b32_e32 v11, v0
	v_mov_b32_e32 v12, v0
	v_mov_b32_e32 v13, v0
	v_mov_b32_e32 v14, v0
	v_mov_b32_e32 v15, v0
	v_mov_b32_e32 v16, v0
	v_mov_b32_e32 v17, v0
	v_mov_b32_e32 v18, v0
	v_mov_b32_e32 v19, v0
	v_mov_b32_e32 v20, v0
	v_mov_b32_e32 v21, v0
	v_mov_b32_e32 v22, v0
	v_mov_b32_e32 v23, v0
	v_mov_b32_e32 v24, v0
	v_mov_b32_e32 v25, v0
	v_mov_b32_e32 v26, v0
	v_mov_b32_e32 v27, v0
	v_mov_b32_e32 v28, v0
	v_mov_b32_e32 v29, v0
	v_mov_b32_e32 v30, v0
	v_mov_b32_e32 v31, v0
	v_mov_b32_e32 v32, v0
	v_mov_b32_e32 v33, v0
	v_mov_b32_e32 v34, v0
	v_mov_b32_e32 v35, v0
	v_mov_b32_e32 v36, v0
	v_mov_b32_e32 v37, v0
	v_mov_b32_e32 v38, v0
	v_mov_b32_e32 v39, v0
	v_mov_b32_e32 v40, v0
	v_mov_b32_e32 v41, v0
	v_mov_b32_e32 v42, v0
	v_mov_b32_e32 v43, v0
	v_mov_b32_e32 v44, v0
	v_mov_b32_e32 v45, v0
	v_mov_b32_e32 v46, v0
	v_mov_b32_e32 v47, v0
	v_mov_b32_e32 v48, v0
	v_mov_b32_e32 v49, v0
	v_mov_b32_e32 v50, v0
	v_mov_b32_e32 v51, v0
	v_mov_b32_e32 v52, v0
	v_mov_b32_e32 v53, v0
	v_mov_b32_e32 v54, v0
	v_mov_b32_e32 v55, v0
	v_mov_b32_e32 v56, v0
	v_mov_b32_e32 v57, v0
	v_mov_b32_e32 v58, v0
	v_mov_b32_e32 v59, v0
	v_mov_b32_e32 v60, v0
	v_mov_b32_e32 v61, v0
	v_mov_b32_e32 v62, v0
	v_mov_b32_e32 v63, v0
	s_add_u32 m0, s61, 0x0
	s_nop 0
	global_load_lds_dwordx4 v64, s[56:57]
	s_add_u32 m0, s61, 0x1000
	s_nop 0
	global_load_lds_dwordx4 v65, s[56:57]
	s_add_u32 m0, s61, 0x2000
	s_nop 0
	global_load_lds_dwordx4 v66, s[56:57]
	s_add_u32 m0, s61, 0x3000
	s_nop 0
	global_load_lds_dwordx4 v67, s[56:57]
	s_add_u32 m0, s61, 0x8000
	s_nop 0
	global_load_lds_dwordx4 v64, s[58:59]
	s_add_u32 m0, s61, 0x9000
	s_nop 0
	global_load_lds_dwordx4 v65, s[58:59]
	s_add_u32 m0, s61, 0xa000
	s_nop 0
	global_load_lds_dwordx4 v66, s[58:59]
	s_add_u32 m0, s61, 0xb000
	s_nop 0
	global_load_lds_dwordx4 v67, s[58:59]
	s_add_u32 s56, s56, 0x80
	s_addc_u32 s57, s57, 0
	s_add_u32 s58, s58, 0x80
	s_addc_u32 s59, s59, 0
	s_add_u32 m0, s61, 0x4000
	s_nop 0
	global_load_lds_dwordx4 v64, s[56:57]
	s_add_u32 m0, s61, 0x5000
	s_nop 0
	global_load_lds_dwordx4 v65, s[56:57]
	s_add_u32 m0, s61, 0x6000
	s_nop 0
	global_load_lds_dwordx4 v66, s[56:57]
	s_add_u32 m0, s61, 0x7000
	s_nop 0
	global_load_lds_dwordx4 v67, s[56:57]
	s_add_u32 m0, s61, 0xc000
	s_nop 0
	global_load_lds_dwordx4 v64, s[58:59]
	s_add_u32 m0, s61, 0xd000
	s_nop 0
	global_load_lds_dwordx4 v65, s[58:59]
	s_add_u32 m0, s61, 0xe000
	s_nop 0
	global_load_lds_dwordx4 v66, s[58:59]
	s_add_u32 m0, s61, 0xf000
	s_nop 0
	global_load_lds_dwordx4 v67, s[58:59]
	s_add_u32 s56, s56, 0x80
	s_addc_u32 s57, s57, 0
	s_add_u32 s58, s58, 0x80
	s_addc_u32 s59, s59, 0
	s_waitcnt vmcnt(8)
	s_barrier
	ds_read_b128 v[186:189], v111 offset:0
	ds_read_b128 v[190:193], v111 offset:4096
	ds_read_b128 v[194:197], v112 offset:32768
	ds_read_b128 v[198:201], v112 offset:36864
	ds_read_b128 v[202:205], v113 offset:0
	ds_read_b128 v[206:209], v113 offset:4096
	ds_read_b128 v[210:213], v114 offset:32768
	ds_read_b128 v[214:217], v114 offset:36864
	ds_read_b128 v[218:221], v115 offset:0
	ds_read_b128 v[222:225], v115 offset:4096
	ds_read_b128 v[226:229], v116 offset:32768
	ds_read_b128 v[230:233], v116 offset:36864
	s_mov_b32 s60, 0
.Lgm_loop_E:
	ds_read_b128 v[234:237], v117 offset:0
	ds_read_b128 v[238:241], v117 offset:4096
	ds_read_b128 v[242:245], v118 offset:32768
	ds_read_b128 v[246:249], v118 offset:36864
	s_waitcnt lgkmcnt(12)
	v_mfma_f32_32x32x16_bf16 v[32:47], v[186:189], v[194:197], v[32:47]
	v_mfma_f32_32x32x16_bf16 v[48:63], v[186:189], v[198:201], v[48:63]
	v_mfma_f32_32x32x16_bf16 v[0:15], v[190:193], v[194:197], v[0:15]
	v_mfma_f32_32x32x16_bf16 v[16:31], v[190:193], v[198:201], v[16:31]
	s_waitcnt vmcnt(0) lgkmcnt(0)
	s_barrier
	s_cmp_lt_u32 s60, 14
	s_cbranch_scc0 .Lgm_nodma0_E
	ds_read_b128 v[186:189], v111 offset:16384
	s_add_u32 m0, s61, 0x0
	s_nop 0
	global_load_lds_dwordx4 v64, s[56:57]
	v_mfma_f32_32x32x16_bf16 v[32:47], v[202:205], v[210:213], v[32:47]
	ds_read_b128 v[190:193], v111 offset:20480
	s_add_u32 m0, s61, 0x1000
	s_nop 0
	global_load_lds_dwordx4 v65, s[56:57]
	v_mfma_f32_32x32x16_bf16 v[48:63], v[202:205], v[214:217], v[48:63]
	ds_read_b128 v[194:197], v112 offset:49152
	s_add_u32 m0, s61, 0x2000
	s_nop 0
	global_load_lds_dwordx4 v66, s[56:57]
	v_mfma_f32_32x32x16_bf16 v[0:15], v[206:209], v[210:213], v[0:15]
	ds_read_b128 v[198:201], v112 offset:53248
	s_add_u32 m0, s61, 0x3000
	s_nop 0
	global_load_lds_dwordx4 v67, s[56:57]
	v_mfma_f32_32x32x16_bf16 v[16:31], v[206:209], v[214:217], v[16:31]
	ds_read_b128 v[202:205], v113 offset:16384
	s_add_u32 m0, s61, 0x8000
	s_nop 0
	global_load_lds_dwordx4 v64, s[58:59]
	v_mfma_f32_32x32x16_bf16 v[32:47], v[218:221], v[226:229], v[32:47]
	ds_read_b128 v[206:209], v113 offset:20480
	s_add_u32 m0, s61, 0x9000
	s_nop 0
	global_load_lds_dwordx4 v65, s[58:59]
	v_mfma_f32_32x32x16_bf16 v[48:63], v[218:221], v[230:233], v[48:63]
	ds_read_b128 v[210:213], v114 offset:49152
	s_add_u32 m0, s61, 0xa000
	s_nop 0
	global_load_lds_dwordx4 v66, s[58:59]
	v_mfma_f32_32x32x16_bf16 v[0:15], v[222:225], v[226:229], v[0:15]
	ds_read_b128 v[214:217], v114 offset:53248
	s_add_u32 m0, s61, 0xb000
	s_nop 0
	global_load_lds_dwordx4 v67, s[58:59]
	v_mfma_f32_32x32x16_bf16 v[16:31], v[222:225], v[230:233], v[16:31]
	ds_read_b128 v[218:221], v115 offset:16384
	s_add_u32 s56, s56, 0x80
	s_addc_u32 s57, s57, 0
	s_add_u32 s58, s58, 0x80
	s_addc_u32 s59, s59, 0
	v_mfma_f32_32x32x16_bf16 v[32:47], v[234:237], v[242:245], v[32:47]
	ds_read_b128 v[222:225], v115 offset:20480
	v_mfma_f32_32x32x16_bf16 v[48:63], v[234:237], v[246:249], v[48:63]
	ds_read_b128 v[226:229], v116 offset:49152
	v_mfma_f32_32x32x16_bf16 v[0:15], v[238:241], v[242:245], v[0:15]
	ds_read_b128 v[230:233], v116 offset:53248
	v_mfma_f32_32x32x16_bf16 v[16:31], v[238:241], v[246:249], v[16:31]
	s_branch .Lgm_join0_E
.Lgm_nodma0_E:
	ds_read_b128 v[186:189], v111 offset:16384
	v_mfma_f32_32x32x16_bf16 v[32:47], v[202:205], v[210:213], v[32:47]
	ds_read_b128 v[190:193], v111 offset:20480
	v_mfma_f32_32x32x16_bf16 v[48:63], v[202:205], v[214:217], v[48:63]
	ds_read_b128 v[194:197], v112 offset:49152
	v_mfma_f32_32x32x16_bf16 v[0:15], v[206:209], v[210:213], v[0:15]
	ds_read_b128 v[198:201], v112 offset:53248
	v_mfma_f32_32x32x16_bf16 v[16:31], v[206:209], v[214:217], v[16:31]
	ds_read_b128 v[202:205], v113 offset:16384
	v_mfma_f32_32x32x16_bf16 v[32:47], v[218:221], v[226:229], v[32:47]
	ds_read_b128 v[206:209], v113 offset:20480
	v_mfma_f32_32x32x16_bf16 v[48:63], v[218:221], v[230:233], v[48:63]
	ds_read_b128 v[210:213], v114 offset:49152
	v_mfma_f32_32x32x16_bf16 v[0:15], v[222:225], v[226:229], v[0:15]
	ds_read_b128 v[214:217], v114 offset:53248
	v_mfma_f32_32x32x16_bf16 v[16:31], v[222:225], v[230:233], v[16:31]
	ds_read_b128 v[218:221], v115 offset:16384
	v_mfma_f32_32x32x16_bf16 v[32:47], v[234:237], v[242:245], v[32:47]
	ds_read_b128 v[222:225], v115 offset:20480
	v_mfma_f32_32x32x16_bf16 v[48:63], v[234:237], v[246:249], v[48:63]
	ds_read_b128 v[226:229], v116 offset:49152
	v_mfma_f32_32x32x16_bf16 v[0:15], v[238:241], v[242:245], v[0:15]
	ds_read_b128 v[230:233], v116 offset:53248
	v_mfma_f32_32x32x16_bf16 v[16:31], v[238:241], v[246:249], v[16:31]
.Lgm_join0_E:
	ds_read_b128 v[234:237], v117 offset:16384
	ds_read_b128 v[238:241], v117 offset:20480
	ds_read_b128 v[242:245], v118 offset:49152
	ds_read_b128 v[246:249], v118 offset:53248
	s_waitcnt lgkmcnt(12)
	v_mfma_f32_32x32x16_bf16 v[32:47], v[186:189], v[194:197], v[32:47]
	v_mfma_f32_32x32x16_bf16 v[48:63], v[186:189], v[198:201], v[48:63]
	v_mfma_f32_32x32x16_bf16 v[0:15], v[190:193], v[194:197], v[0:15]
	v_mfma_f32_32x32x16_bf16 v[16:31], v[190:193], v[198:201], v[16:31]
	s_waitcnt vmcnt(0) lgkmcnt(0)
	s_barrier
	s_cmp_lt_u32 s60, 14
	s_cbranch_scc0 .Lgm_nodma1_E
	ds_read_b128 v[186:189], v111 offset:0
	s_add_u32 m0, s61, 0x4000
	s_nop 0
	global_load_lds_dwordx4 v64, s[56:57]
	v_mfma_f32_32x32x16_bf16 v[32:47], v[202:205], v[210:213], v[32:47]
	ds_read_b128 v[190:193], v111 offset:4096
	s_add_u32 m0, s61, 0x5000
	s_nop 0
	global_load_lds_dwordx4 v65, s[56:57]
	v_mfma_f32_32x32x16_bf16 v[48:63], v[202:205], v[214:217], v[48:63]
	ds_read_b128 v[194:197], v112 offset:32768
	s_add_u32 m0, s61, 0x6000
	s_nop 0
	global_load_lds_dwordx4 v66, s[56:57]
	v_mfma_f32_32x32x16_bf16 v[0:15], v[206:209], v[210:213], v[0:15]
	ds_read_b128 v[198:201], v112 offset:36864
	s_add_u32 m0, s61, 0x7000
	s_nop 0
	global_load_lds_dwordx4 v67, s[56:57]
	v_mfma_f32_32x32x16_bf16 v[16:31], v[206:209], v[214:217], v[16:31]
	ds_read_b128 v[202:205], v113 offset:0
	s_add_u32 m0, s61, 0xc000
	s_nop 0
	global_load_lds_dwordx4 v64, s[58:59]
	v_mfma_f32_32x32x16_bf16 v[32:47], v[218:221], v[226:229], v[32:47]
	ds_read_b128 v[206:209], v113 offset:4096
	s_add_u32 m0, s61, 0xd000
	s_nop 0
	global_load_lds_dwordx4 v65, s[58:59]
	v_mfma_f32_32x32x16_bf16 v[48:63], v[218:221], v[230:233], v[48:63]
	ds_read_b128 v[210:213], v114 offset:32768
	s_add_u32 m0, s61, 0xe000
	s_nop 0
	global_load_lds_dwordx4 v66, s[58:59]
	v_mfma_f32_32x32x16_bf16 v[0:15], v[222:225], v[226:229], v[0:15]
	ds_read_b128 v[214:217], v114 offset:36864
	s_add_u32 m0, s61, 0xf000
	s_nop 0
	global_load_lds_dwordx4 v67, s[58:59]
	v_mfma_f32_32x32x16_bf16 v[16:31], v[222:225], v[230:233], v[16:31]
	ds_read_b128 v[218:221], v115 offset:0
	s_add_u32 s56, s56, 0x80
	s_addc_u32 s57, s57, 0
	s_add_u32 s58, s58, 0x80
	s_addc_u32 s59, s59, 0
	v_mfma_f32_32x32x16_bf16 v[32:47], v[234:237], v[242:245], v[32:47]
	ds_read_b128 v[222:225], v115 offset:4096
	v_mfma_f32_32x32x16_bf16 v[48:63], v[234:237], v[246:249], v[48:63]
	ds_read_b128 v[226:229], v116 offset:32768
	v_mfma_f32_32x32x16_bf16 v[0:15], v[238:241], v[242:245], v[0:15]
	ds_read_b128 v[230:233], v116 offset:36864
	v_mfma_f32_32x32x16_bf16 v[16:31], v[238:241], v[246:249], v[16:31]
	s_branch .Lgm_join1_E
.Lgm_nodma1_E:
	ds_read_b128 v[186:189], v111 offset:0
	v_mfma_f32_32x32x16_bf16 v[32:47], v[202:205], v[210:213], v[32:47]
	ds_read_b128 v[190:193], v111 offset:4096
	v_mfma_f32_32x32x16_bf16 v[48:63], v[202:205], v[214:217], v[48:63]
	ds_read_b128 v[194:197], v112 offset:32768
	v_mfma_f32_32x32x16_bf16 v[0:15], v[206:209], v[210:213], v[0:15]
	ds_read_b128 v[198:201], v112 offset:36864
	v_mfma_f32_32x32x16_bf16 v[16:31], v[206:209], v[214:217], v[16:31]
	ds_read_b128 v[202:205], v113 offset:0
	v_mfma_f32_32x32x16_bf16 v[32:47], v[218:221], v[226:229], v[32:47]
	ds_read_b128 v[206:209], v113 offset:4096
	v_mfma_f32_32x32x16_bf16 v[48:63], v[218:221], v[230:233], v[48:63]
	ds_read_b128 v[210:213], v114 offset:32768
	v_mfma_f32_32x32x16_bf16 v[0:15], v[222:225], v[226:229], v[0:15]
	ds_read_b128 v[214:217], v114 offset:36864
	v_mfma_f32_32x32x16_bf16 v[16:31], v[222:225], v[230:233], v[16:31]
	ds_read_b128 v[218:221], v115 offset:0
	v_mfma_f32_32x32x16_bf16 v[32:47], v[234:237], v[242:245], v[32:47]
	ds_read_b128 v[222:225], v115 offset:4096
	v_mfma_f32_32x32x16_bf16 v[48:63], v[234:237], v[246:249], v[48:63]
	ds_read_b128 v[226:229], v116 offset:32768
	v_mfma_f32_32x32x16_bf16 v[0:15], v[238:241], v[242:245], v[0:15]
	ds_read_b128 v[230:233], v116 offset:36864
	v_mfma_f32_32x32x16_bf16 v[16:31], v[238:241], v[246:249], v[16:31]
.Lgm_join1_E:
	s_add_u32 s60, s60, 2
	s_cmp_lt_u32 s60, 16
	s_cbranch_scc1 .Lgm_loop_E
	s_waitcnt lgkmcnt(0)
	s_barrier
	s_nop 7
	s_cmpk_lt_i32 s45, 0x400
	v_or_b32_e32 v98, s6, v105
	v_add_lshl_u32 v88, v98, v106, 11
	v_or_b32_e32 v96, s0, v108
	v_ashrrev_i32_e32 v97, 31, v96
	v_lshl_add_u64 v[80:81], s[0:1], 1, v[94:95]
	v_lshl_add_u64 v[82:83], v[80:81], 0, v[88:89]
	v_add_lshl_u32 v88, v98, v107, 11
	v_lshl_add_u64 v[134:135], v[80:81], 0, v[88:89]
	v_or_b32_e32 v86, 32, v98
	v_add_lshl_u32 v88, v86, v106, 11
	v_lshl_add_u64 v[136:137], v[80:81], 0, v[88:89]
	v_add_lshl_u32 v88, v86, v107, 11
	v_lshl_add_u64 v[84:85], v[96:97], 1, s[42:43]
	v_lshl_add_u64 v[138:139], v[80:81], 0, v[88:89]
	v_add_lshl_u32 v88, s6, v109, 11
	v_lshl_add_u64 v[100:101], v[84:85], 0, v[88:89]
	v_add_lshl_u32 v88, s6, v110, 11
	v_lshl_add_u64 v[102:103], v[84:85], 0, v[88:89]
	v_add_lshl_u32 v88, s4, v109, 11
	v_lshl_add_u64 v[98:99], v[84:85], 0, v[88:89]
	v_add_lshl_u32 v88, s4, v110, 11
	v_lshl_add_u64 v[96:97], v[84:85], 0, v[88:89]
	global_load_dwordx4 v[84:87], v[82:83], off nt
	global_load_dwordx4 v[80:83], v[134:135], off nt
	global_load_dwordx4 v[76:79], v[136:137], off nt
	global_load_dwordx4 v[72:75], v[138:139], off nt
	ds_write2_b32 v119, v32, v48 offset1:32
	ds_write2_b32 v119, v33, v49 offset0:132 offset1:164
	ds_write2_b32 v122, v34, v50 offset0:8 offset1:40
	ds_write2_b32 v122, v35, v51 offset0:140 offset1:172
	ds_write2_b32 v123, v36, v52 offset0:32 offset1:64
	ds_write2_b32 v123, v37, v53 offset0:164 offset1:196
	ds_write2_b32 v124, v38, v54 offset0:40 offset1:72
	ds_write2_b32 v124, v39, v55 offset0:172 offset1:204
	ds_write2_b32 v125, v40, v56 offset0:64 offset1:96
	ds_write2_b32 v125, v41, v57 offset0:196 offset1:228
	ds_write2_b32 v126, v42, v58 offset0:72 offset1:104
	ds_write2_b32 v126, v43, v59 offset0:204 offset1:236
	ds_write2_b32 v127, v44, v60 offset0:96 offset1:128
	ds_write2_b32 v129, v45, v61 offset0:100 offset1:132
	ds_write2_b32 v130, v46, v62 offset0:104 offset1:136
	ds_write2_b32 v131, v47, v63 offset0:108 offset1:140
	s_waitcnt lgkmcnt(0)
	s_barrier
	ds_read_b128 v[32:35], v120 offset:128
	ds_read_b128 v[40:43], v120
	ds_read_b128 v[44:47], v120 offset:16
	ds_read_b128 v[36:39], v120 offset:144
	ds_read_b128 v[48:51], v121 offset:128
	s_waitcnt lgkmcnt(4)
	v_mul_f32_e32 v64, 0xbfb8aa3b, v32
	v_mul_f32_e32 v66, 0xbfb8aa3b, v34
	v_mul_f32_e32 v65, 0xbfb8aa3b, v33
	s_waitcnt lgkmcnt(3)
	v_mov_b32_e32 v32, v40
	v_mov_b32_e32 v33, v42
	v_mov_b32_e32 v42, v41
	v_exp_f32_e32 v40, v64
	v_exp_f32_e32 v41, v66
	v_mul_f32_e32 v67, 0xbfb8aa3b, v35
	s_waitcnt lgkmcnt(2)
	v_mov_b32_e32 v34, v44
	v_mov_b32_e32 v35, v46
	v_mov_b32_e32 v46, v45
	v_exp_f32_e32 v44, v65
	v_exp_f32_e32 v45, v67
	ds_read_b128 v[52:55], v121 offset:144
	s_waitcnt lgkmcnt(2)
	v_mul_f32_e32 v68, 0xbfb8aa3b, v36
	v_mul_f32_e32 v70, 0xbfb8aa3b, v38
	s_waitcnt lgkmcnt(1)
	v_mul_f32_e32 v88, 0xbfb8aa3b, v48
	v_mul_f32_e32 v133, 0xbfb8aa3b, v49
	v_exp_f32_e32 v48, v68
	v_exp_f32_e32 v49, v70
	v_pk_add_f32 v[40:41], v[40:41], 1.0 op_sel_hi:[1,0]
	v_mul_f32_e32 v69, 0xbfb8aa3b, v37
	v_mul_f32_e32 v71, 0xbfb8aa3b, v39
	ds_read_b128 v[56:59], v121
	v_mul_f32_e32 v134, 0xbfb8aa3b, v50
	v_mul_f32_e32 v135, 0xbfb8aa3b, v51
	v_exp_f32_e32 v50, v69
	v_exp_f32_e32 v51, v71
	v_pk_add_f32 v[44:45], v[44:45], 1.0 op_sel_hi:[1,0]
	s_waitcnt lgkmcnt(1)
	v_mul_f32_e32 v136, 0xbfb8aa3b, v52
	v_mul_f32_e32 v137, 0xbfb8aa3b, v53
	v_exp_f32_e32 v52, v88
	v_exp_f32_e32 v53, v134
	v_pk_add_f32 v[48:49], v[48:49], 1.0 op_sel_hi:[1,0]
	ds_read_b128 v[60:63], v121 offset:16
	v_mul_f32_e32 v138, 0xbfb8aa3b, v54
	v_mul_f32_e32 v139, 0xbfb8aa3b, v55
	v_exp_f32_e32 v54, v133
	v_exp_f32_e32 v55, v135
	v_pk_add_f32 v[50:51], v[50:51], 1.0 op_sel_hi:[1,0]
	s_waitcnt lgkmcnt(1)
	v_mov_b32_e32 v36, v56
	v_exp_f32_e32 v56, v136
	v_mov_b32_e32 v37, v58
	v_mov_b32_e32 v58, v57
	v_exp_f32_e32 v57, v138
	v_pk_add_f32 v[52:53], v[52:53], 1.0 op_sel_hi:[1,0]
	s_waitcnt lgkmcnt(0)
	v_mov_b32_e32 v38, v60
	v_mov_b32_e32 v39, v62
	v_mov_b32_e32 v62, v61
	v_exp_f32_e32 v60, v137
	v_exp_f32_e32 v61, v139
	v_pk_add_f32 v[54:55], v[54:55], 1.0 op_sel_hi:[1,0]
	v_pk_add_f32 v[56:57], v[56:57], 1.0 op_sel_hi:[1,0]
	s_mov_b64 vcc, s[30:31]
	v_rcp_f32_e32 v41, v41
	s_nop 0
	s_mov_b64 vcc, s[28:29]
	v_pk_add_f32 v[60:61], v[60:61], 1.0 op_sel_hi:[1,0]
	v_rcp_f32_e32 v40, v40
	s_nop 0
	s_mov_b64 vcc, s[26:27]
	v_pk_mul_f32 v[64:65], v[32:33], v[40:41]
	s_mov_b64 vcc, s[24:25]
	v_rcp_f32_e32 v33, v45
	s_nop 0
	v_rcp_f32_e32 v32, v44
	s_nop 0
	s_mov_b64 vcc, s[22:23]
	v_pk_mul_f32 v[66:67], v[42:43], v[32:33]
	s_mov_b64 vcc, s[20:21]
	v_rcp_f32_e32 v33, v49
	s_nop 0
	v_rcp_f32_e32 v32, v48
	s_nop 0
	s_mov_b64 vcc, s[16:17]
	v_pk_mul_f32 v[48:49], v[34:35], v[32:33]
	s_mov_b64 vcc, s[14:15]
	v_rcp_f32_e32 v33, v51
	s_nop 0
	v_rcp_f32_e32 v32, v50
	s_nop 0
	s_mov_b64 vcc, s[12:13]
	v_pk_mul_f32 v[50:51], v[46:47], v[32:33]
	s_mov_b64 vcc, s[10:11]
	v_rcp_f32_e32 v33, v53
	s_nop 0
	v_rcp_f32_e32 v32, v52
	s_nop 0
	s_mov_b64 vcc, s[8:9]
	v_pk_mul_f32 v[52:53], v[36:37], v[32:33]
	s_mov_b64 vcc, s[6:7]
	v_rcp_f32_e32 v33, v55
	s_nop 0
	v_rcp_f32_e32 v32, v54
	s_nop 0
	s_mov_b64 vcc, s[4:5]
	v_pk_mul_f32 v[54:55], v[58:59], v[32:33]
	s_mov_b64 vcc, s[34:35]
	v_rcp_f32_e32 v33, v57
	s_nop 0
	v_rcp_f32_e32 v32, v56
	s_nop 0
	s_mov_b64 vcc, s[0:1]
	v_pk_mul_f32 v[56:57], v[38:39], v[32:33]
	v_rcp_f32_e32 v33, v61
	s_nop 0
	v_rcp_f32_e32 v32, v60
	s_nop 0
	v_pk_mul_f32 v[58:59], v[62:63], v[32:33]
	s_waitcnt vmcnt(3)
	v_lshlrev_b32_e32 v61, 16, v85
	v_lshlrev_b32_e32 v60, 16, v84
	v_and_b32_e32 v63, 0xffff0000, v85
	v_and_b32_e32 v62, 0xffff0000, v84
	v_lshlrev_b32_e32 v69, 16, v87
	v_lshlrev_b32_e32 v68, 16, v86
	v_and_b32_e32 v71, 0xffff0000, v87
	v_and_b32_e32 v70, 0xffff0000, v86
	s_waitcnt vmcnt(2)
	v_lshlrev_b32_e32 v85, 16, v81
	v_lshlrev_b32_e32 v84, 16, v80
	v_and_b32_e32 v81, 0xffff0000, v81
	v_and_b32_e32 v80, 0xffff0000, v80
	v_lshlrev_b32_e32 v87, 16, v83
	v_lshlrev_b32_e32 v86, 16, v82
	v_and_b32_e32 v83, 0xffff0000, v83
	v_and_b32_e32 v82, 0xffff0000, v82
	v_pk_mul_f32 v[60:61], v[64:65], v[60:61]
	v_pk_mul_f32 v[62:63], v[66:67], v[62:63]
	v_pk_mul_f32 v[48:49], v[48:49], v[68:69]
	v_pk_mul_f32 v[50:51], v[50:51], v[70:71]
	v_pk_mul_f32 v[54:55], v[54:55], v[80:81]
	v_pk_mul_f32 v[56:57], v[56:57], v[86:87]
	v_pk_mul_f32 v[58:59], v[58:59], v[82:83]
	s_waitcnt vmcnt(1)
	v_lshlrev_b32_e32 v47, 16, v77
	v_lshlrev_b32_e32 v46, 16, v76
	v_and_b32_e32 v45, 0xffff0000, v77
	v_and_b32_e32 v44, 0xffff0000, v76
	v_lshlrev_b32_e32 v43, 16, v79
	v_lshlrev_b32_e32 v42, 16, v78
	v_and_b32_e32 v41, 0xffff0000, v79
	v_and_b32_e32 v40, 0xffff0000, v78
	s_waitcnt vmcnt(0)
	v_lshlrev_b32_e32 v35, 16, v75
	v_lshlrev_b32_e32 v34, 16, v74
	v_and_b32_e32 v33, 0xffff0000, v75
	v_and_b32_e32 v32, 0xffff0000, v74
	v_pk_mul_f32 v[52:53], v[52:53], v[84:85]
	v_and_b32_sdwa v64, v61, v132 dst_sel:DWORD dst_unused:UNUSED_PAD src0_sel:WORD_1 src1_sel:DWORD
	v_and_b32_sdwa v65, v60, v132 dst_sel:DWORD dst_unused:UNUSED_PAD src0_sel:WORD_1 src1_sel:DWORD
	v_and_b32_sdwa v66, v63, v132 dst_sel:DWORD dst_unused:UNUSED_PAD src0_sel:WORD_1 src1_sel:DWORD
	v_and_b32_sdwa v67, v62, v132 dst_sel:DWORD dst_unused:UNUSED_PAD src0_sel:WORD_1 src1_sel:DWORD
	v_and_b32_sdwa v68, v49, v132 dst_sel:DWORD dst_unused:UNUSED_PAD src0_sel:WORD_1 src1_sel:DWORD
	v_and_b32_sdwa v69, v48, v132 dst_sel:DWORD dst_unused:UNUSED_PAD src0_sel:WORD_1 src1_sel:DWORD
	v_and_b32_sdwa v70, v51, v132 dst_sel:DWORD dst_unused:UNUSED_PAD src0_sel:WORD_1 src1_sel:DWORD
	v_and_b32_sdwa v71, v50, v132 dst_sel:DWORD dst_unused:UNUSED_PAD src0_sel:WORD_1 src1_sel:DWORD
	v_and_b32_sdwa v74, v55, v132 dst_sel:DWORD dst_unused:UNUSED_PAD src0_sel:WORD_1 src1_sel:DWORD
	v_and_b32_sdwa v75, v54, v132 dst_sel:DWORD dst_unused:UNUSED_PAD src0_sel:WORD_1 src1_sel:DWORD
	v_and_b32_sdwa v76, v57, v132 dst_sel:DWORD dst_unused:UNUSED_PAD src0_sel:WORD_1 src1_sel:DWORD
	v_and_b32_sdwa v77, v56, v132 dst_sel:DWORD dst_unused:UNUSED_PAD src0_sel:WORD_1 src1_sel:DWORD
	v_and_b32_sdwa v78, v59, v132 dst_sel:DWORD dst_unused:UNUSED_PAD src0_sel:WORD_1 src1_sel:DWORD
	v_and_b32_sdwa v79, v58, v132 dst_sel:DWORD dst_unused:UNUSED_PAD src0_sel:WORD_1 src1_sel:DWORD
	v_lshlrev_b32_e32 v39, 16, v73
	v_lshlrev_b32_e32 v38, 16, v72
	v_and_b32_e32 v37, 0xffff0000, v73
	v_and_b32_e32 v36, 0xffff0000, v72
	v_and_b32_sdwa v72, v53, v132 dst_sel:DWORD dst_unused:UNUSED_PAD src0_sel:WORD_1 src1_sel:DWORD
	v_and_b32_sdwa v73, v52, v132 dst_sel:DWORD dst_unused:UNUSED_PAD src0_sel:WORD_1 src1_sel:DWORD
	v_add3_u32 v60, v60, v65, s44
	v_add3_u32 v61, v61, v64, s44
	v_add3_u32 v63, v63, v66, s44
	v_add3_u32 v62, v62, v67, s44
	v_add3_u32 v64, v48, v69, s44
	v_add3_u32 v65, v49, v68, s44
	v_add3_u32 v48, v51, v70, s44
	v_add3_u32 v49, v50, v71, s44
	v_add3_u32 v50, v55, v74, s44
	v_add3_u32 v51, v54, v75, s44
	v_add3_u32 v54, v56, v77, s44
	v_add3_u32 v55, v57, v76, s44
	v_add3_u32 v56, v59, v78, s44
	v_add3_u32 v57, v58, v79, s44
	v_add3_u32 v52, v52, v73, s44
	v_add3_u32 v53, v53, v72, s44
	v_and_b32_e32 v58, 0xffff0000, v63
	v_and_b32_e32 v59, 0xffff0000, v62
	v_and_b32_e32 v62, 0xffff0000, v48
	v_and_b32_e32 v63, 0xffff0000, v49
	v_and_b32_e32 v66, 0xffff0000, v50
	v_and_b32_e32 v67, 0xffff0000, v51
	v_and_b32_e32 v56, 0xffff0000, v56
	v_and_b32_e32 v57, 0xffff0000, v57
	v_or_b32_sdwa v49, v58, v61 dst_sel:DWORD dst_unused:UNUSED_PAD src0_sel:DWORD src1_sel:WORD_1
	v_or_b32_sdwa v48, v59, v60 dst_sel:DWORD dst_unused:UNUSED_PAD src0_sel:DWORD src1_sel:WORD_1
	v_or_b32_sdwa v51, v62, v65 dst_sel:DWORD dst_unused:UNUSED_PAD src0_sel:DWORD src1_sel:WORD_1
	v_or_b32_sdwa v50, v63, v64 dst_sel:DWORD dst_unused:UNUSED_PAD src0_sel:DWORD src1_sel:WORD_1
	v_or_b32_sdwa v53, v66, v53 dst_sel:DWORD dst_unused:UNUSED_PAD src0_sel:DWORD src1_sel:WORD_1
	v_or_b32_sdwa v52, v67, v52 dst_sel:DWORD dst_unused:UNUSED_PAD src0_sel:DWORD src1_sel:WORD_1
	v_or_b32_sdwa v55, v56, v55 dst_sel:DWORD dst_unused:UNUSED_PAD src0_sel:DWORD src1_sel:WORD_1
	v_or_b32_sdwa v54, v57, v54 dst_sel:DWORD dst_unused:UNUSED_PAD src0_sel:DWORD src1_sel:WORD_1
	global_store_dwordx4 v[100:101], v[48:51], off
	global_store_dwordx4 v[102:103], v[52:55], off
	s_barrier
	ds_write2_b32 v119, v0, v16 offset1:32
	ds_write2_b32 v119, v1, v17 offset0:132 offset1:164
	ds_write2_b32 v122, v2, v18 offset0:8 offset1:40
	ds_write2_b32 v122, v3, v19 offset0:140 offset1:172
	ds_write2_b32 v123, v4, v20 offset0:32 offset1:64
	ds_write2_b32 v123, v5, v21 offset0:164 offset1:196
	ds_write2_b32 v124, v6, v22 offset0:40 offset1:72
	ds_write2_b32 v124, v7, v23 offset0:172 offset1:204
	ds_write2_b32 v125, v8, v24 offset0:64 offset1:96
	ds_write2_b32 v125, v9, v25 offset0:196 offset1:228
	ds_write2_b32 v126, v10, v26 offset0:72 offset1:104
	ds_write2_b32 v126, v11, v27 offset0:204 offset1:236
	ds_write2_b32 v127, v12, v28 offset0:96 offset1:128
	ds_write2_b32 v129, v13, v29 offset0:100 offset1:132
	ds_write2_b32 v130, v14, v30 offset0:104 offset1:136
	ds_write2_b32 v131, v15, v31 offset0:108 offset1:140
	s_waitcnt lgkmcnt(0)
	s_barrier
	ds_read_b128 v[8:11], v120 offset:128
	ds_read_b128 v[12:15], v120 offset:144
	ds_read_b128 v[4:7], v121
	ds_read_b128 v[0:3], v121 offset:16
	ds_read_b128 v[16:19], v120
	s_waitcnt lgkmcnt(4)
	v_mul_f32_e32 v48, 0xbfb8aa3b, v8
	v_mul_f32_e32 v50, 0xbfb8aa3b, v10
	s_waitcnt lgkmcnt(3)
	v_mul_f32_e32 v52, 0xbfb8aa3b, v12
	v_mul_f32_e32 v53, 0xbfb8aa3b, v13
	s_waitcnt lgkmcnt(2)
	v_mov_b32_e32 v12, v4
	v_mov_b32_e32 v13, v6
	v_mov_b32_e32 v6, v5
	s_waitcnt lgkmcnt(1)
	v_mov_b32_e32 v4, v0
	v_mov_b32_e32 v5, v2
	v_mov_b32_e32 v2, v1
	v_exp_f32_e32 v0, v48
	v_exp_f32_e32 v1, v50
	ds_read_b128 v[20:23], v120 offset:16
	v_mul_f32_e32 v49, 0xbfb8aa3b, v9
	v_mul_f32_e32 v51, 0xbfb8aa3b, v11
	ds_read_b128 v[24:27], v121 offset:128
	v_mul_f32_e32 v54, 0xbfb8aa3b, v14
	v_mul_f32_e32 v55, 0xbfb8aa3b, v15
	v_exp_f32_e32 v14, v49
	v_exp_f32_e32 v15, v51
	s_waitcnt lgkmcnt(2)
	v_mov_b32_e32 v8, v16
	v_mov_b32_e32 v9, v18
	v_mov_b32_e32 v18, v17
	v_exp_f32_e32 v16, v52
	v_exp_f32_e32 v17, v54
	v_pk_add_f32 v[0:1], v[0:1], 1.0 op_sel_hi:[1,0]
	ds_read_b128 v[28:31], v121 offset:144
	s_waitcnt lgkmcnt(2)
	v_mov_b32_e32 v10, v20
	v_mov_b32_e32 v11, v22
	v_mov_b32_e32 v22, v21
	v_exp_f32_e32 v20, v53
	v_exp_f32_e32 v21, v55
	v_pk_add_f32 v[14:15], v[14:15], 1.0 op_sel_hi:[1,0]
	s_waitcnt lgkmcnt(1)
	v_mul_f32_e32 v24, 0xbfb8aa3b, v24
	v_mul_f32_e32 v25, 0xbfb8aa3b, v25
	v_mul_f32_e32 v56, 0xbfb8aa3b, v26
	v_exp_f32_e32 v24, v24
	v_exp_f32_e32 v26, v25
	v_exp_f32_e32 v25, v56
	v_pk_add_f32 v[16:17], v[16:17], 1.0 op_sel_hi:[1,0]
	v_mul_f32_e32 v27, 0xbfb8aa3b, v27
	v_exp_f32_e32 v27, v27
	v_pk_add_f32 v[20:21], v[20:21], 1.0 op_sel_hi:[1,0]
	s_waitcnt lgkmcnt(0)
	v_mul_f32_e32 v28, 0xbfb8aa3b, v28
	v_mul_f32_e32 v29, 0xbfb8aa3b, v29
	v_mul_f32_e32 v57, 0xbfb8aa3b, v30
	v_exp_f32_e32 v28, v28
	v_exp_f32_e32 v30, v29
	v_exp_f32_e32 v29, v57
	v_pk_add_f32 v[24:25], v[24:25], 1.0 op_sel_hi:[1,0]
	v_mul_f32_e32 v31, 0xbfb8aa3b, v31
	v_exp_f32_e32 v31, v31
	v_pk_add_f32 v[26:27], v[26:27], 1.0 op_sel_hi:[1,0]
	v_pk_add_f32 v[28:29], v[28:29], 1.0 op_sel_hi:[1,0]
	s_mov_b64 vcc, s[30:31]
	v_rcp_f32_e32 v1, v1
	s_nop 0
	s_mov_b64 vcc, s[28:29]
	v_pk_add_f32 v[30:31], v[30:31], 1.0 op_sel_hi:[1,0]
	v_rcp_f32_e32 v0, v0
	s_nop 0
	s_mov_b64 vcc, s[26:27]
	v_pk_mul_f32 v[0:1], v[8:9], v[0:1]
	s_mov_b64 vcc, s[24:25]
	v_rcp_f32_e32 v9, v15
	s_nop 0
	v_rcp_f32_e32 v8, v14
	s_nop 0
	s_mov_b64 vcc, s[22:23]
	v_pk_mul_f32 v[0:1], v[0:1], v[46:47]
	v_pk_mul_f32 v[8:9], v[18:19], v[8:9]
	v_rcp_f32_e32 v15, v17
	s_nop 0
	s_mov_b64 vcc, s[20:21]
	v_and_b32_sdwa v18, v1, v132 dst_sel:DWORD dst_unused:UNUSED_PAD src0_sel:WORD_1 src1_sel:DWORD
	v_and_b32_sdwa v19, v0, v132 dst_sel:DWORD dst_unused:UNUSED_PAD src0_sel:WORD_1 src1_sel:DWORD
	v_pk_mul_f32 v[8:9], v[8:9], v[44:45]
	v_rcp_f32_e32 v14, v16
	s_nop 0
	s_mov_b64 vcc, s[16:17]
	v_add3_u32 v17, v0, v19, s44
	v_add3_u32 v18, v1, v18, s44
	v_and_b32_sdwa v19, v9, v132 dst_sel:DWORD dst_unused:UNUSED_PAD src0_sel:WORD_1 src1_sel:DWORD
	v_pk_mul_f32 v[0:1], v[10:11], v[14:15]
	s_mov_b64 vcc, s[14:15]
	v_and_b32_sdwa v44, v8, v132 dst_sel:DWORD dst_unused:UNUSED_PAD src0_sel:WORD_1 src1_sel:DWORD
	v_rcp_f32_e32 v11, v21
	s_nop 0
	v_add3_u32 v9, v9, v19, s44
	v_rcp_f32_e32 v10, v20
	s_nop 0
	s_mov_b64 vcc, s[12:13]
	v_add3_u32 v8, v8, v44, s44
	v_pk_mul_f32 v[0:1], v[0:1], v[42:43]
	v_and_b32_e32 v9, 0xffff0000, v9
	v_pk_mul_f32 v[10:11], v[22:23], v[10:11]
	v_rcp_f32_e32 v15, v25
	s_nop 0
	s_mov_b64 vcc, s[10:11]
	v_and_b32_e32 v8, 0xffff0000, v8
	v_and_b32_sdwa v16, v1, v132 dst_sel:DWORD dst_unused:UNUSED_PAD src0_sel:WORD_1 src1_sel:DWORD
	v_and_b32_sdwa v19, v0, v132 dst_sel:DWORD dst_unused:UNUSED_PAD src0_sel:WORD_1 src1_sel:DWORD
	v_or_b32_sdwa v9, v9, v18 dst_sel:DWORD dst_unused:UNUSED_PAD src0_sel:DWORD src1_sel:WORD_1
	v_pk_mul_f32 v[10:11], v[10:11], v[40:41]
	v_rcp_f32_e32 v14, v24
	s_nop 0
	s_mov_b64 vcc, s[8:9]
	v_or_b32_sdwa v8, v8, v17 dst_sel:DWORD dst_unused:UNUSED_PAD src0_sel:DWORD src1_sel:WORD_1
	v_add3_u32 v17, v0, v19, s44
	v_add3_u32 v16, v1, v16, s44
	v_and_b32_sdwa v19, v11, v132 dst_sel:DWORD dst_unused:UNUSED_PAD src0_sel:WORD_1 src1_sel:DWORD
	v_pk_mul_f32 v[0:1], v[12:13], v[14:15]
	s_mov_b64 vcc, s[6:7]
	v_and_b32_sdwa v20, v10, v132 dst_sel:DWORD dst_unused:UNUSED_PAD src0_sel:WORD_1 src1_sel:DWORD
	v_rcp_f32_e32 v13, v27
	s_nop 0
	v_add3_u32 v11, v11, v19, s44
	v_pk_mul_f32 v[0:1], v[0:1], v[38:39]
	v_rcp_f32_e32 v12, v26
	s_nop 0
	s_mov_b64 vcc, s[4:5]
	v_add3_u32 v10, v10, v20, s44
	v_and_b32_e32 v11, 0xffff0000, v11
	v_pk_mul_f32 v[6:7], v[6:7], v[12:13]
	v_and_b32_sdwa v12, v1, v132 dst_sel:DWORD dst_unused:UNUSED_PAD src0_sel:WORD_1 src1_sel:DWORD
	v_rcp_f32_e32 v13, v29
	s_nop 0
	s_mov_b64 vcc, s[34:35]
	v_and_b32_e32 v10, 0xffff0000, v10
	v_and_b32_sdwa v15, v0, v132 dst_sel:DWORD dst_unused:UNUSED_PAD src0_sel:WORD_1 src1_sel:DWORD
	v_or_b32_sdwa v11, v11, v16 dst_sel:DWORD dst_unused:UNUSED_PAD src0_sel:DWORD src1_sel:WORD_1
	v_add3_u32 v16, v1, v12, s44
	v_rcp_f32_e32 v12, v28
	s_nop 0
	s_mov_b64 vcc, s[0:1]
	v_or_b32_sdwa v10, v10, v17 dst_sel:DWORD dst_unused:UNUSED_PAD src0_sel:DWORD src1_sel:WORD_1
	v_pk_mul_f32 v[6:7], v[6:7], v[36:37]
	v_add3_u32 v15, v0, v15, s44
	v_pk_mul_f32 v[0:1], v[4:5], v[12:13]
	global_store_dwordx4 v[98:99], v[8:11], off
	v_rcp_f32_e32 v5, v31
	s_nop 0
	v_rcp_f32_e32 v4, v30
	s_nop 0
	v_and_b32_sdwa v8, v7, v132 dst_sel:DWORD dst_unused:UNUSED_PAD src0_sel:WORD_1 src1_sel:DWORD
	v_and_b32_sdwa v9, v6, v132 dst_sel:DWORD dst_unused:UNUSED_PAD src0_sel:WORD_1 src1_sel:DWORD
	v_add3_u32 v8, v7, v8, s44
	v_add3_u32 v9, v6, v9, s44
	v_pk_mul_f32 v[6:7], v[0:1], v[34:35]
	v_pk_mul_f32 v[2:3], v[2:3], v[4:5]
	v_and_b32_sdwa v4, v7, v132 dst_sel:DWORD dst_unused:UNUSED_PAD src0_sel:WORD_1 src1_sel:DWORD
	v_and_b32_sdwa v5, v6, v132 dst_sel:DWORD dst_unused:UNUSED_PAD src0_sel:WORD_1 src1_sel:DWORD
	v_pk_mul_f32 v[2:3], v[2:3], v[32:33]
	v_add3_u32 v5, v6, v5, s44
	v_add3_u32 v4, v7, v4, s44
	v_and_b32_sdwa v6, v3, v132 dst_sel:DWORD dst_unused:UNUSED_PAD src0_sel:WORD_1 src1_sel:DWORD
	v_and_b32_sdwa v7, v2, v132 dst_sel:DWORD dst_unused:UNUSED_PAD src0_sel:WORD_1 src1_sel:DWORD
	v_add3_u32 v3, v3, v6, s44
	v_add3_u32 v2, v2, v7, s44
	v_and_b32_e32 v0, 0xffff0000, v8
	v_and_b32_e32 v8, 0xffff0000, v9
	v_and_b32_e32 v3, 0xffff0000, v3
	v_and_b32_e32 v2, 0xffff0000, v2
	v_or_b32_sdwa v1, v0, v16 dst_sel:DWORD dst_unused:UNUSED_PAD src0_sel:DWORD src1_sel:WORD_1
	v_or_b32_sdwa v0, v8, v15 dst_sel:DWORD dst_unused:UNUSED_PAD src0_sel:DWORD src1_sel:WORD_1
	v_or_b32_sdwa v3, v3, v4 dst_sel:DWORD dst_unused:UNUSED_PAD src0_sel:DWORD src1_sel:WORD_1
	v_or_b32_sdwa v2, v2, v5 dst_sel:DWORD dst_unused:UNUSED_PAD src0_sel:DWORD src1_sel:WORD_1
	global_store_dwordx4 v[96:97], v[0:3], off
	s_barrier
	s_cbranch_scc1 .LBB0_864
